# prep phase: conditioning vectors touched with wide loads at the adaLN job start so the silu-table loop hits cache
# speedup vs baseline: 1.0776x; 1.0007x over previous
.LBB0_77:
	s_and_b64 vcc, exec, s[18:19]
	s_cbranch_vccz .LBB0_56
	v_lshlrev_b32_e32 v178, 4, v184
	v_add_u32_e32 v179, 0x2000, v178
	v_add_u32_e32 v180, 0x4000, v178
	v_add_u32_e32 v181, 0x6000, v178
	s_mov_b32 s20, s53
	s_mov_b32 s21, s54
	global_load_dwordx4 v[248:251], v178, s[20:21]
	global_load_dwordx4 v[248:251], v179, s[20:21]
	global_load_dwordx4 v[248:251], v180, s[20:21]
	global_load_dwordx4 v[248:251], v181, s[20:21]
	s_mov_b32 s20, s49
	s_mov_b32 s21, s50
	v_cmp_gt_u32_e32 vcc, 0x100, v184
	s_and_saveexec_b64 s[18:19], vcc
	global_load_dwordx4 v[248:251], v178, s[20:21]
	s_or_b64 exec, exec, s[18:19]
	v_mov_b32_e32 v4, 0
	v_mov_b64_e32 v[2:3], v[184:185]
	s_and_saveexec_b64 s[44:45], s[10:11]
	s_cbranch_execz .LBB0_83
	s_mov_b32 s75, 0
	s_mov_b64 s[46:47], 0
	v_mov_b32_e32 v4, v119
	v_mov_b64_e32 v[2:3], v[184:185]
